# v32 + rwkv_prep out-loop: each unit's loads issued at the start of the previous unit's compute into spare registers, copied in place behind a counted wait that skips the store drain
# speedup vs baseline: 1.0105x; 1.0105x over previous
; DI float sigmoidf_(float x) { return __builtin_amdgcn_rcpf(1.f + __expf(-x)); }
; DI void rwkv_prep_item(KA a, const int l, LAS unsigned char* lds, const int tile) {
;     ...
;         for (int ct = 0; ct < 4; ++ct) { const int c4 = hd * 64 + ct * 16 + 4 * fq; const size_t ro = (size_t)tk * 256 + c4;
;             const f32x4 mur = *(const f32x4*)(mu + c4), muv4 = *(const f32x4*)(mu + 512 + c4), w04 = *(const f32x4*)(w0 + c4), a04 = *(const f32x4*)(a0 + c4), kk4 = *(const f32x4*)(kkw + c4), ka4 = *(const f32x4*)(kaw + c4);
;             f32x4 v04 = ZERO4; if (l == 1) v04 = *(const f32x4*)(v0 + c4);
;             const bf16* hpr = H + (size_t)tk * HP + C_RR + c4; const bf16* hpv = H + (size_t)tk * HP + C_RV + c4;
;             const v2u cr = *(const v2u*)hpr, cv = *(const v2u*)hpv; v2u pr = {0u, 0u}, pvv = {0u, 0u}; if (!first) { pr = *(const v2u*)(hpr - HP); pvv = *(const v2u*)(hpv - HP); }
;             v2u vf2 = {0u, 0u}; if (l == 1) vf2 = *(const v2u*)(VF + ro);
;             const float cr_[4] = {bflo(cr.x), bfhi(cr.x), bflo(cr.y), bfhi(cr.y)}, pr_[4] = {bflo(pr.x), bfhi(pr.x), bflo(pr.y), bfhi(pr.y)};
;             const float cv_[4] = {bflo(cv.x), bfhi(cv.x), bflo(cv.y), bfhi(cv.y)}, pv_[4] = {bflo(pvv.x), bfhi(pvv.x), bflo(pvv.y), bfhi(pvv.y)}, vf_[4] = {bflo(vf2.x), bfhi(vf2.x), bflo(vf2.y), bfhi(vf2.y)};
;             float o_r[4], o_k[4], o_v[4], o_a[4], o_b[4]; f32x4 o_w;
; #pragma unroll
;             for (int j = 0; j < 4; ++j) { const float r = cr_[j] + (pr_[j] - cr_[j]) * mur[j]; float v = cv_[j] + (pv_[j] - cv_[j]) * muv4[j];
;                 if (l == 1) v = v + (vf_[j] - v) * sigmoidf_(v04[j] + accv[ct][rt][j]);
.LBB0_370:
	s_waitcnt vmcnt(0)
	global_load_dwordx4 v[182:185], v[130:131], off offset:128
	global_load_dwordx4 v[216:219], v[130:131], off offset:2176
	global_load_dwordx4 v[212:215], v[120:121], off offset:128
	global_load_dwordx4 v[208:211], v[122:123], off offset:128
	global_load_dwordx4 v[246:249], v[128:129], off offset:128
	global_load_dwordx4 v[150:153], v[124:125], off offset:128
	v_mov_b32_e32 v186, 0
	s_and_b64 vcc, exec, s[40:41]
	v_mov_b32_e32 v220, 0
	v_mov_b32_e32 v221, 0
	v_mov_b32_e32 v222, 0
	v_mov_b32_e32 v223, 0
	s_cbranch_vccnz .LBB0_382
	global_load_dwordx4 v[220:223], v[126:127], off offset:128
.LBB0_382:
	global_load_dwordx2 v[224:225], v[136:137], off offset:2144
	global_load_dwordx2 v[226:227], v[136:137], off offset:3168
	v_mov_b32_e32 v187, 0
	v_mov_b32_e32 v228, 0
	v_mov_b32_e32 v229, 0
	s_and_saveexec_b64 s[0:1], s[42:43]
	s_cbranch_execz .LBB0_384
	s_mov_b64 s[2:3], 0x860
	v_lshl_add_u64 v[250:251], v[136:137], 0, s[2:3]
	v_add_co_u32_e32 v250, vcc, 0xfffff000, v250
	s_nop 1
	v_addc_co_u32_e32 v251, vcc, -1, v251, vcc
	global_load_dwordx2 v[186:187], v[250:251], off offset:-3072
	global_load_dwordx2 v[228:229], v[136:137], off offset:-4000
.LBB0_384:
	s_or_b64 exec, exec, s[0:1]
	v_or_b32_e32 v250, 32, v132
	v_ashrrev_i32_e32 v251, 31, v250
	v_lshl_add_u64 v[242:243], v[138:139], 0, v[250:251]
	v_mov_b32_e32 v230, 0
	s_and_b64 vcc, exec, s[40:41]
	v_lshl_add_u64 v[206:207], v[242:243], 1, s[50:51]
	v_mov_b32_e32 v231, 0
	s_cbranch_vccnz .Lrp_e0
	global_load_dwordx2 v[230:231], v[206:207], off
.Lrp_e0:
	v_lshlrev_b32_e32 v149, 16, v144
	v_lshlrev_b32_e32 v148, 16, v142
	v_sub_f32_e32 v149, v149, v148
	s_and_b64 vcc, exec, s[40:41]
	v_fmac_f32_e32 v148, v104, v149
	s_cbranch_vccnz .LBB0_372
	v_add_f32_e32 v88, v88, v108
	v_mul_f32_e32 v88, 0xbfb8aa3b, v88
	v_exp_f32_e32 v88, v88
	v_lshlrev_b32_e32 v104, 16, v146
	v_sub_f32_e32 v104, v104, v148
	v_add_f32_e32 v88, 1.0, v88
	v_rcp_f32_e32 v88, v88
	s_nop 0
	v_fmac_f32_e32 v148, v88, v104

; DI float sigmoidf_(float x) { return __builtin_amdgcn_rcpf(1.f + __expf(-x)); }
; DI void rwkv_prep_item(KA a, const int l, LAS unsigned char* lds, const int tile) {
;     ...
;         for (int ct = 0; ct < 4; ++ct) { const int c4 = hd * 64 + ct * 16 + 4 * fq; const size_t ro = (size_t)tk * 256 + c4;
;             const f32x4 mur = *(const f32x4*)(mu + c4), muv4 = *(const f32x4*)(mu + 512 + c4), w04 = *(const f32x4*)(w0 + c4), a04 = *(const f32x4*)(a0 + c4), kk4 = *(const f32x4*)(kkw + c4), ka4 = *(const f32x4*)(kaw + c4);
;             f32x4 v04 = ZERO4; if (l == 1) v04 = *(const f32x4*)(v0 + c4);
;             const bf16* hpr = H + (size_t)tk * HP + C_RR + c4; const bf16* hpv = H + (size_t)tk * HP + C_RV + c4;
;             const v2u cr = *(const v2u*)hpr, cv = *(const v2u*)hpv; v2u pr = {0u, 0u}, pvv = {0u, 0u}; if (!first) { pr = *(const v2u*)(hpr - HP); pvv = *(const v2u*)(hpv - HP); }
;             v2u vf2 = {0u, 0u}; if (l == 1) vf2 = *(const v2u*)(VF + ro);
;             const float cr_[4] = {bflo(cr.x), bfhi(cr.x), bflo(cr.y), bfhi(cr.y)}, pr_[4] = {bflo(pr.x), bfhi(pr.x), bflo(pr.y), bfhi(pr.y)};
;             const float cv_[4] = {bflo(cv.x), bfhi(cv.x), bflo(cv.y), bfhi(cv.y)}, pv_[4] = {bflo(pvv.x), bfhi(pvv.x), bflo(pvv.y), bfhi(pvv.y)}, vf_[4] = {bflo(vf2.x), bfhi(vf2.x), bflo(vf2.y), bfhi(vf2.y)};
;             float o_r[4], o_k[4], o_v[4], o_a[4], o_b[4]; f32x4 o_w;
; #pragma unroll
;             for (int j = 0; j < 4; ++j) { const float r = cr_[j] + (pr_[j] - cr_[j]) * mur[j]; float v = cv_[j] + (pv_[j] - cv_[j]) * muv4[j];
;                 if (l == 1) v = v + (vf_[j] - v) * sigmoidf_(v04[j] + accv[ct][rt][j]);
.LBB0_380:
	s_waitcnt vmcnt(6)
	v_mov_b32_e32 v68, v150
	v_mov_b32_e32 v69, v151
	v_mov_b32_e32 v70, v152
	v_mov_b32_e32 v71, v153
	v_mov_b32_e32 v72, v246
	v_mov_b32_e32 v73, v247
	v_mov_b32_e32 v74, v248
	v_mov_b32_e32 v75, v249
	v_mov_b32_e32 v80, v182
	v_mov_b32_e32 v81, v183
	v_mov_b32_e32 v82, v184
	v_mov_b32_e32 v83, v185
	v_mov_b32_e32 v84, v208
	v_mov_b32_e32 v85, v209
	v_mov_b32_e32 v86, v210
	v_mov_b32_e32 v87, v211
	v_mov_b32_e32 v88, v212
	v_mov_b32_e32 v89, v213
	v_mov_b32_e32 v90, v214
	v_mov_b32_e32 v91, v215
	v_mov_b32_e32 v92, v216
	v_mov_b32_e32 v93, v217
	v_mov_b32_e32 v94, v218
	v_mov_b32_e32 v95, v219
	v_mov_b32_e32 v96, v220
	v_mov_b32_e32 v97, v221
	v_mov_b32_e32 v98, v222
	v_mov_b32_e32 v99, v223
	v_mov_b32_e32 v100, v250
	v_mov_b32_e32 v101, v251
	v_mov_b32_e32 v102, v206
	v_mov_b32_e32 v103, v207
	v_mov_b32_e32 v104, v186
	v_mov_b32_e32 v105, v187
	v_mov_b32_e32 v106, v242
	v_mov_b32_e32 v107, v243
	v_mov_b32_e32 v108, v224
	v_mov_b32_e32 v109, v225
	v_mov_b32_e32 v110, v226
	v_mov_b32_e32 v111, v227
	v_mov_b32_e32 v114, v228
	v_mov_b32_e32 v115, v229
	v_mov_b32_e32 v116, v230
	v_mov_b32_e32 v117, v231
.LBB0_386:
	global_load_dwordx4 v[182:185], v[130:131], off offset:192
	global_load_dwordx4 v[216:219], v[130:131], off offset:2240
	global_load_dwordx4 v[212:215], v[120:121], off offset:192
	global_load_dwordx4 v[208:211], v[122:123], off offset:192
	global_load_dwordx4 v[246:249], v[128:129], off offset:192
	global_load_dwordx4 v[150:153], v[124:125], off offset:192
	v_mov_b32_e32 v186, 0
	s_and_b64 vcc, exec, s[40:41]
	v_mov_b32_e32 v220, 0
	v_mov_b32_e32 v221, 0
	v_mov_b32_e32 v222, 0
	v_mov_b32_e32 v223, 0
	s_cbranch_vccnz .LBB0_398
	global_load_dwordx4 v[220:223], v[126:127], off offset:192
.LBB0_398:
	global_load_dwordx2 v[224:225], v[136:137], off offset:2176
	global_load_dwordx2 v[226:227], v[136:137], off offset:3200
	v_mov_b32_e32 v187, 0
	v_mov_b32_e32 v228, 0
	v_mov_b32_e32 v229, 0
	s_and_saveexec_b64 s[0:1], s[42:43]
	s_cbranch_execz .LBB0_400
	s_mov_b64 s[2:3], 0x880
	v_lshl_add_u64 v[250:251], v[136:137], 0, s[2:3]
	v_add_co_u32_e32 v250, vcc, 0xfffff000, v250
	s_nop 1
	v_addc_co_u32_e32 v251, vcc, -1, v251, vcc
	global_load_dwordx2 v[186:187], v[250:251], off offset:-3072
	global_load_dwordx2 v[228:229], v[136:137], off offset:-3968
.LBB0_400:
	s_or_b64 exec, exec, s[0:1]
	v_or_b32_e32 v250, 48, v132
	v_ashrrev_i32_e32 v251, 31, v250
	v_lshl_add_u64 v[242:243], v[138:139], 0, v[250:251]
	v_mov_b32_e32 v230, 0
	s_and_b64 vcc, exec, s[40:41]
	v_lshl_add_u64 v[206:207], v[242:243], 1, s[50:51]
	v_mov_b32_e32 v231, 0
	s_cbranch_vccnz .Lrp_e1
	global_load_dwordx2 v[230:231], v[206:207], off
.Lrp_e1:
	v_lshlrev_b32_e32 v119, 16, v114
	v_lshlrev_b32_e32 v118, 16, v110
	v_sub_f32_e32 v119, v119, v118
	s_and_b64 vcc, exec, s[40:41]
	v_fmac_f32_e32 v118, v92, v119
	s_cbranch_vccnz .LBB0_388
	v_add_f32_e32 v76, v76, v96
	v_mul_f32_e32 v76, 0xbfb8aa3b, v76
	v_exp_f32_e32 v76, v76
	v_lshlrev_b32_e32 v92, 16, v116
	v_sub_f32_e32 v92, v92, v118
	v_add_f32_e32 v76, 1.0, v76
	v_rcp_f32_e32 v76, v76
	s_nop 0
	v_fmac_f32_e32 v118, v76, v92

; DI float sigmoidf_(float x) { return __builtin_amdgcn_rcpf(1.f + __expf(-x)); }
; DI void rwkv_prep_item(KA a, const int l, LAS unsigned char* lds, const int tile) {
;     ...
;     for (int rt = 0; rt < 2; ++rt) { const int tk = t0 + 32 * th + 16 * rt + fr; const bool first = (tk & (SEQ - 1)) == 0;
; #pragma unroll
;         for (int ct = 0; ct < 4; ++ct) { const int c4 = hd * 64 + ct * 16 + 4 * fq; const size_t ro = (size_t)tk * 256 + c4;
;             const f32x4 mur = *(const f32x4*)(mu + c4), muv4 = *(const f32x4*)(mu + 512 + c4), w04 = *(const f32x4*)(w0 + c4), a04 = *(const f32x4*)(a0 + c4), kk4 = *(const f32x4*)(kkw + c4), ka4 = *(const f32x4*)(kaw + c4);
;             f32x4 v04 = ZERO4; if (l == 1) v04 = *(const f32x4*)(v0 + c4);
;             const bf16* hpr = H + (size_t)tk * HP + C_RR + c4; const bf16* hpv = H + (size_t)tk * HP + C_RV + c4;
;             const v2u cr = *(const v2u*)hpr, cv = *(const v2u*)hpv; v2u pr = {0u, 0u}, pvv = {0u, 0u}; if (!first) { pr = *(const v2u*)(hpr - HP); pvv = *(const v2u*)(hpv - HP); }
;             v2u vf2 = {0u, 0u}; if (l == 1) vf2 = *(const v2u*)(VF + ro);
;             const float cr_[4] = {bflo(cr.x), bfhi(cr.x), bflo(cr.y), bfhi(cr.y)}, pr_[4] = {bflo(pr.x), bfhi(pr.x), bflo(pr.y), bfhi(pr.y)};
;             const float cv_[4] = {bflo(cv.x), bfhi(cv.x), bflo(cv.y), bfhi(cv.y)}, pv_[4] = {bflo(pvv.x), bfhi(pvv.x), bflo(pvv.y), bfhi(pvv.y)}, vf_[4] = {bflo(vf2.x), bfhi(vf2.x), bflo(vf2.y), bfhi(vf2.y)};
;             float o_r[4], o_k[4], o_v[4], o_a[4], o_b[4]; f32x4 o_w;
; #pragma unroll
;             for (int j = 0; j < 4; ++j) { const float r = cr_[j] + (pr_[j] - cr_[j]) * mur[j]; float v = cv_[j] + (pv_[j] - cv_[j]) * muv4[j];
;                 if (l == 1) v = v + (vf_[j] - v) * sigmoidf_(v04[j] + accv[ct][rt][j]);
.LBB0_396:
	s_waitcnt vmcnt(6)
	v_mov_b32_e32 v60, v150
	v_mov_b32_e32 v61, v151
	v_mov_b32_e32 v62, v152
	v_mov_b32_e32 v63, v153
	v_mov_b32_e32 v64, v246
	v_mov_b32_e32 v65, v247
	v_mov_b32_e32 v66, v248
	v_mov_b32_e32 v67, v249
	v_mov_b32_e32 v68, v182
	v_mov_b32_e32 v69, v183
	v_mov_b32_e32 v70, v184
	v_mov_b32_e32 v71, v185
	v_mov_b32_e32 v72, v208
	v_mov_b32_e32 v73, v209
	v_mov_b32_e32 v74, v210
	v_mov_b32_e32 v75, v211
	v_mov_b32_e32 v76, v212
	v_mov_b32_e32 v77, v213
	v_mov_b32_e32 v78, v214
	v_mov_b32_e32 v79, v215
	v_mov_b32_e32 v80, v216
	v_mov_b32_e32 v81, v217
	v_mov_b32_e32 v82, v218
	v_mov_b32_e32 v83, v219
	v_mov_b32_e32 v84, v220
	v_mov_b32_e32 v85, v221
	v_mov_b32_e32 v86, v222
	v_mov_b32_e32 v87, v223
	v_mov_b32_e32 v88, v250
	v_mov_b32_e32 v89, v251
	v_mov_b32_e32 v90, v206
	v_mov_b32_e32 v91, v207
	v_mov_b32_e32 v92, v186
	v_mov_b32_e32 v93, v187
	v_mov_b32_e32 v94, v242
	v_mov_b32_e32 v95, v243
	v_mov_b32_e32 v96, v224
	v_mov_b32_e32 v97, v225
	v_mov_b32_e32 v98, v226
	v_mov_b32_e32 v99, v227
	v_mov_b32_e32 v102, v228
	v_mov_b32_e32 v103, v229
	v_mov_b32_e32 v104, v230
	v_mov_b32_e32 v105, v231
.LBB0_402:
	global_load_dwordx4 v[182:185], v[130:131], off
	global_load_dwordx4 v[216:219], v[130:131], off offset:2048
	global_load_dwordx4 v[212:215], v[120:121], off
	global_load_dwordx4 v[208:211], v[122:123], off
	global_load_dwordx4 v[246:249], v[128:129], off
	global_load_dwordx4 v[150:153], v[124:125], off
	v_mov_b32_e32 v244, 0
	s_and_b64 vcc, exec, s[40:41]
	v_mov_b32_e32 v220, 0
	v_mov_b32_e32 v221, 0
	v_mov_b32_e32 v222, 0
	v_mov_b32_e32 v223, 0
	s_cbranch_vccnz .LBB0_414
	global_load_dwordx4 v[220:223], v[126:127], off
.LBB0_414:
	v_or_b32_e32 v192, 16, v134
	v_mov_b64_e32 v[250:251], s[16:17]
	s_movk_i32 s0, 0x1c00
	v_mad_u64_u32 v[250:251], s[0:1], v192, s0, v[250:251]
	v_lshl_add_u64 v[250:251], v[132:133], 1, v[250:251]
	v_add_co_u32_e32 v206, vcc, 0xfffff000, v250
	v_mov_b32_e32 v255, 0
	s_nop 0
	v_addc_co_u32_e32 v207, vcc, -1, v251, vcc
	global_load_dwordx2 v[186:187], v[250:251], off offset:2080
	global_load_dwordx2 v[224:225], v[250:251], off offset:3104
	global_load_dwordx2 v[242:243], v[206:207], off offset:-992
	global_load_dwordx2 v[226:227], v[250:251], off offset:-4064
.Lrp_e2:
	v_lshlrev_b32_e32 v107, 16, v102
	v_lshlrev_b32_e32 v106, 16, v98
	v_sub_f32_e32 v107, v107, v106
	s_and_b64 vcc, exec, s[40:41]
	v_fmac_f32_e32 v106, v80, v107
	s_cbranch_vccnz .LBB0_404
	v_add_f32_e32 v56, v56, v84
	v_mul_f32_e32 v56, 0xbfb8aa3b, v56
	v_exp_f32_e32 v56, v56
	v_lshlrev_b32_e32 v80, 16, v104
	v_sub_f32_e32 v80, v80, v106
	v_add_f32_e32 v56, 1.0, v56
	v_rcp_f32_e32 v56, v56
	s_nop 0
	v_fmac_f32_e32 v106, v56, v80

; DI float sigmoidf_(float x) { return __builtin_amdgcn_rcpf(1.f + __expf(-x)); }
; DI void rwkv_prep_item(KA a, const int l, LAS unsigned char* lds, const int tile) {
;     ...
;     for (int rt = 0; rt < 2; ++rt) { const int tk = t0 + 32 * th + 16 * rt + fr; const bool first = (tk & (SEQ - 1)) == 0;
; #pragma unroll
;         for (int ct = 0; ct < 4; ++ct) { const int c4 = hd * 64 + ct * 16 + 4 * fq; const size_t ro = (size_t)tk * 256 + c4;
;             const f32x4 mur = *(const f32x4*)(mu + c4), muv4 = *(const f32x4*)(mu + 512 + c4), w04 = *(const f32x4*)(w0 + c4), a04 = *(const f32x4*)(a0 + c4), kk4 = *(const f32x4*)(kkw + c4), ka4 = *(const f32x4*)(kaw + c4);
;             f32x4 v04 = ZERO4; if (l == 1) v04 = *(const f32x4*)(v0 + c4);
;             const bf16* hpr = H + (size_t)tk * HP + C_RR + c4; const bf16* hpv = H + (size_t)tk * HP + C_RV + c4;
;             const v2u cr = *(const v2u*)hpr, cv = *(const v2u*)hpv; v2u pr = {0u, 0u}, pvv = {0u, 0u}; if (!first) { pr = *(const v2u*)(hpr - HP); pvv = *(const v2u*)(hpv - HP); }
;             v2u vf2 = {0u, 0u}; if (l == 1) vf2 = *(const v2u*)(VF + ro);
;             const float cr_[4] = {bflo(cr.x), bfhi(cr.x), bflo(cr.y), bfhi(cr.y)}, pr_[4] = {bflo(pr.x), bfhi(pr.x), bflo(pr.y), bfhi(pr.y)};
;             const float cv_[4] = {bflo(cv.x), bfhi(cv.x), bflo(cv.y), bfhi(cv.y)}, pv_[4] = {bflo(pvv.x), bfhi(pvv.x), bflo(pvv.y), bfhi(pvv.y)}, vf_[4] = {bflo(vf2.x), bfhi(vf2.x), bflo(vf2.y), bfhi(vf2.y)};
;             float o_r[4], o_k[4], o_v[4], o_a[4], o_b[4]; f32x4 o_w;
; #pragma unroll
;             for (int j = 0; j < 4; ++j) { const float r = cr_[j] + (pr_[j] - cr_[j]) * mur[j]; float v = cv_[j] + (pv_[j] - cv_[j]) * muv4[j];
;                 if (l == 1) v = v + (vf_[j] - v) * sigmoidf_(v04[j] + accv[ct][rt][j]);
.LBB0_412:
	s_waitcnt vmcnt(6)
	v_mov_b32_e32 v48, v150
	v_mov_b32_e32 v49, v151
	v_mov_b32_e32 v50, v152
	v_mov_b32_e32 v51, v153
	v_mov_b32_e32 v52, v246
	v_mov_b32_e32 v53, v247
	v_mov_b32_e32 v54, v248
	v_mov_b32_e32 v55, v249
	v_mov_b32_e32 v56, v182
	v_mov_b32_e32 v57, v183
	v_mov_b32_e32 v58, v184
	v_mov_b32_e32 v59, v185
	v_mov_b32_e32 v60, v208
	v_mov_b32_e32 v61, v209
	v_mov_b32_e32 v62, v210
	v_mov_b32_e32 v63, v211
	v_mov_b32_e32 v64, v212
	v_mov_b32_e32 v65, v213
	v_mov_b32_e32 v66, v214
	v_mov_b32_e32 v67, v215
	v_mov_b32_e32 v68, v216
	v_mov_b32_e32 v69, v217
	v_mov_b32_e32 v70, v218
	v_mov_b32_e32 v71, v219
	v_mov_b32_e32 v72, v220
	v_mov_b32_e32 v73, v221
	v_mov_b32_e32 v74, v222
	v_mov_b32_e32 v75, v223
	v_mov_b32_e32 v76, v250
	v_mov_b32_e32 v77, v251
	v_mov_b32_e32 v78, v206
	v_mov_b32_e32 v79, v207
	v_mov_b32_e32 v84, v186
	v_mov_b32_e32 v85, v187
	v_mov_b32_e32 v86, v242
	v_mov_b32_e32 v87, v243
	v_mov_b32_e32 v90, v244
	v_mov_b32_e32 v91, v255
	v_mov_b32_e32 v92, v224
	v_mov_b32_e32 v93, v225
	v_mov_b32_e32 v94, v226
	v_mov_b32_e32 v95, v227
	v_lshlrev_b64 v[78:79], 8, v[192:193]
	v_lshl_add_u64 v[82:83], v[78:79], 0, v[132:133]
	s_and_b64 vcc, exec, s[40:41]
	v_lshl_add_u64 v[80:81], v[82:83], 1, s[50:51]
	s_cbranch_vccnz .LBB0_416
	global_load_dwordx2 v[90:91], v[80:81], off
	s_waitcnt vmcnt(0)
.LBB0_416:
	global_load_dwordx4 v[182:185], v[130:131], off offset:64
	global_load_dwordx4 v[216:219], v[130:131], off offset:2112
	global_load_dwordx4 v[212:215], v[120:121], off offset:64
	global_load_dwordx4 v[208:211], v[122:123], off offset:64
	global_load_dwordx4 v[246:249], v[128:129], off offset:64
	global_load_dwordx4 v[150:153], v[124:125], off offset:64
	v_mov_b32_e32 v224, 0
	s_and_b64 vcc, exec, s[40:41]
	v_mov_b32_e32 v220, 0
	v_mov_b32_e32 v221, 0
	v_mov_b32_e32 v222, 0
	v_mov_b32_e32 v223, 0
	s_cbranch_vccnz .LBB0_428
	global_load_dwordx4 v[220:223], v[126:127], off offset:64
.LBB0_428:
	v_add_co_u32_e32 v250, vcc, 0xfffff000, v76
	v_lshl_add_u64 v[206:207], v[78:79], 0, v[112:113]
	s_nop 0
	v_addc_co_u32_e32 v251, vcc, -1, v77, vcc
	global_load_dwordx2 v[186:187], v[76:77], off offset:2112
	global_load_dwordx2 v[226:227], v[76:77], off offset:3136
	global_load_dwordx2 v[242:243], v[250:251], off offset:-960
	global_load_dwordx2 v[228:229], v[76:77], off offset:-4032
	s_and_b64 vcc, exec, s[40:41]
	v_lshl_add_u64 v[250:251], v[206:207], 1, s[50:51]
	v_mov_b32_e32 v225, 0
	s_cbranch_vccnz .Lrp_e3
	global_load_dwordx2 v[224:225], v[250:251], off
.Lrp_e3:
	v_lshlrev_b32_e32 v96, 16, v92
	v_lshlrev_b32_e32 v97, 16, v94
	v_sub_f32_e32 v97, v97, v96
	s_and_b64 vcc, exec, s[40:41]
	v_fmac_f32_e32 v96, v68, v97
	s_cbranch_vccnz .LBB0_418
	v_add_f32_e32 v44, v44, v72
	v_mul_f32_e32 v44, 0xbfb8aa3b, v44
	v_exp_f32_e32 v44, v44
	v_lshlrev_b32_e32 v68, 16, v90
	v_sub_f32_e32 v68, v68, v96
	v_add_f32_e32 v44, 1.0, v44
	v_rcp_f32_e32 v44, v44
	s_nop 0
	v_fmac_f32_e32 v96, v44, v68

; DI float sigmoidf_(float x) { return __builtin_amdgcn_rcpf(1.f + __expf(-x)); }
; DI void rwkv_prep_item(KA a, const int l, LAS unsigned char* lds, const int tile) {
;     ...
;         for (int ct = 0; ct < 4; ++ct) { const int c4 = hd * 64 + ct * 16 + 4 * fq; const size_t ro = (size_t)tk * 256 + c4;
;             const f32x4 mur = *(const f32x4*)(mu + c4), muv4 = *(const f32x4*)(mu + 512 + c4), w04 = *(const f32x4*)(w0 + c4), a04 = *(const f32x4*)(a0 + c4), kk4 = *(const f32x4*)(kkw + c4), ka4 = *(const f32x4*)(kaw + c4);
;             f32x4 v04 = ZERO4; if (l == 1) v04 = *(const f32x4*)(v0 + c4);
;             const bf16* hpr = H + (size_t)tk * HP + C_RR + c4; const bf16* hpv = H + (size_t)tk * HP + C_RV + c4;
;             const v2u cr = *(const v2u*)hpr, cv = *(const v2u*)hpv; v2u pr = {0u, 0u}, pvv = {0u, 0u}; if (!first) { pr = *(const v2u*)(hpr - HP); pvv = *(const v2u*)(hpv - HP); }
;             v2u vf2 = {0u, 0u}; if (l == 1) vf2 = *(const v2u*)(VF + ro);
;             const float cr_[4] = {bflo(cr.x), bfhi(cr.x), bflo(cr.y), bfhi(cr.y)}, pr_[4] = {bflo(pr.x), bfhi(pr.x), bflo(pr.y), bfhi(pr.y)};
;             const float cv_[4] = {bflo(cv.x), bfhi(cv.x), bflo(cv.y), bfhi(cv.y)}, pv_[4] = {bflo(pvv.x), bfhi(pvv.x), bflo(pvv.y), bfhi(pvv.y)}, vf_[4] = {bflo(vf2.x), bfhi(vf2.x), bflo(vf2.y), bfhi(vf2.y)};
;             float o_r[4], o_k[4], o_v[4], o_a[4], o_b[4]; f32x4 o_w;
; #pragma unroll
;             for (int j = 0; j < 4; ++j) { const float r = cr_[j] + (pr_[j] - cr_[j]) * mur[j]; float v = cv_[j] + (pv_[j] - cv_[j]) * muv4[j];
;                 if (l == 1) v = v + (vf_[j] - v) * sigmoidf_(v04[j] + accv[ct][rt][j]);
.LBB0_426:
	s_waitcnt vmcnt(6)
	v_mov_b32_e32 v32, v150
	v_mov_b32_e32 v33, v151
	v_mov_b32_e32 v34, v152
	v_mov_b32_e32 v35, v153
	v_mov_b32_e32 v36, v246
	v_mov_b32_e32 v37, v247
	v_mov_b32_e32 v38, v248
	v_mov_b32_e32 v39, v249
	v_mov_b32_e32 v44, v182
	v_mov_b32_e32 v45, v183
	v_mov_b32_e32 v46, v184
	v_mov_b32_e32 v47, v185
	v_mov_b32_e32 v48, v208
	v_mov_b32_e32 v49, v209
	v_mov_b32_e32 v50, v210
	v_mov_b32_e32 v51, v211
	v_mov_b32_e32 v52, v212
	v_mov_b32_e32 v53, v213
	v_mov_b32_e32 v54, v214
	v_mov_b32_e32 v55, v215
	v_mov_b32_e32 v56, v216
	v_mov_b32_e32 v57, v217
	v_mov_b32_e32 v58, v218
	v_mov_b32_e32 v59, v219
	v_mov_b32_e32 v60, v220
	v_mov_b32_e32 v61, v221
	v_mov_b32_e32 v62, v222
	v_mov_b32_e32 v63, v223
	v_mov_b32_e32 v64, v250
	v_mov_b32_e32 v65, v251
	v_mov_b32_e32 v66, v206
	v_mov_b32_e32 v67, v207
	v_mov_b32_e32 v68, v186
	v_mov_b32_e32 v69, v187
	v_mov_b32_e32 v70, v242
	v_mov_b32_e32 v71, v243
	v_mov_b32_e32 v72, v224
	v_mov_b32_e32 v73, v225
	v_mov_b32_e32 v74, v226
	v_mov_b32_e32 v75, v227
	v_mov_b32_e32 v80, v228
	v_mov_b32_e32 v81, v229
.LBB0_430:
	global_load_dwordx4 v[182:185], v[130:131], off offset:128
	global_load_dwordx4 v[216:219], v[130:131], off offset:2176
	global_load_dwordx4 v[212:215], v[120:121], off offset:128
	global_load_dwordx4 v[208:211], v[122:123], off offset:128
	global_load_dwordx4 v[246:249], v[128:129], off offset:128
	global_load_dwordx4 v[150:153], v[124:125], off offset:128
	v_mov_b32_e32 v224, 0
	s_and_b64 vcc, exec, s[40:41]
	v_mov_b32_e32 v220, 0
	v_mov_b32_e32 v221, 0
	v_mov_b32_e32 v222, 0
	v_mov_b32_e32 v223, 0
	s_cbranch_vccnz .LBB0_442
	global_load_dwordx4 v[220:223], v[126:127], off offset:128
.LBB0_442:
	v_add_co_u32_e32 v250, vcc, 0xfffff000, v76
	v_lshl_add_u64 v[206:207], v[78:79], 0, v[100:101]
	s_nop 0
	v_addc_co_u32_e32 v251, vcc, -1, v77, vcc
	global_load_dwordx2 v[186:187], v[76:77], off offset:2144
	global_load_dwordx2 v[226:227], v[76:77], off offset:3168
	global_load_dwordx2 v[242:243], v[250:251], off offset:-928
	global_load_dwordx2 v[228:229], v[76:77], off offset:-4000
	s_and_b64 vcc, exec, s[40:41]
	v_lshl_add_u64 v[250:251], v[206:207], 1, s[50:51]
	v_mov_b32_e32 v225, 0
	s_cbranch_vccnz .Lrp_e4
	global_load_dwordx2 v[224:225], v[250:251], off
.Lrp_e4:
	v_lshlrev_b32_e32 v82, 16, v74
	v_lshlrev_b32_e32 v83, 16, v80
	v_sub_f32_e32 v83, v83, v82
	s_and_b64 vcc, exec, s[40:41]
	v_fmac_f32_e32 v82, v56, v83
	s_cbranch_vccnz .LBB0_432
	v_add_f32_e32 v40, v40, v60
	v_mul_f32_e32 v40, 0xbfb8aa3b, v40
	v_exp_f32_e32 v40, v40
	v_lshlrev_b32_e32 v56, 16, v72
	v_sub_f32_e32 v56, v56, v82
	v_add_f32_e32 v40, 1.0, v40
	v_rcp_f32_e32 v40, v40
	s_nop 0
	v_fmac_f32_e32 v82, v40, v56

; DI float sigmoidf_(float x) { return __builtin_amdgcn_rcpf(1.f + __expf(-x)); }
; DI void rwkv_prep_item(KA a, const int l, LAS unsigned char* lds, const int tile) {
;     ...
;         for (int ct = 0; ct < 4; ++ct) { const int c4 = hd * 64 + ct * 16 + 4 * fq; const size_t ro = (size_t)tk * 256 + c4;
;             const f32x4 mur = *(const f32x4*)(mu + c4), muv4 = *(const f32x4*)(mu + 512 + c4), w04 = *(const f32x4*)(w0 + c4), a04 = *(const f32x4*)(a0 + c4), kk4 = *(const f32x4*)(kkw + c4), ka4 = *(const f32x4*)(kaw + c4);
;             f32x4 v04 = ZERO4; if (l == 1) v04 = *(const f32x4*)(v0 + c4);
;             const bf16* hpr = H + (size_t)tk * HP + C_RR + c4; const bf16* hpv = H + (size_t)tk * HP + C_RV + c4;
;             const v2u cr = *(const v2u*)hpr, cv = *(const v2u*)hpv; v2u pr = {0u, 0u}, pvv = {0u, 0u}; if (!first) { pr = *(const v2u*)(hpr - HP); pvv = *(const v2u*)(hpv - HP); }
;             v2u vf2 = {0u, 0u}; if (l == 1) vf2 = *(const v2u*)(VF + ro);
;             const float cr_[4] = {bflo(cr.x), bfhi(cr.x), bflo(cr.y), bfhi(cr.y)}, pr_[4] = {bflo(pr.x), bfhi(pr.x), bflo(pr.y), bfhi(pr.y)};
;             const float cv_[4] = {bflo(cv.x), bfhi(cv.x), bflo(cv.y), bfhi(cv.y)}, pv_[4] = {bflo(pvv.x), bfhi(pvv.x), bflo(pvv.y), bfhi(pvv.y)}, vf_[4] = {bflo(vf2.x), bfhi(vf2.x), bflo(vf2.y), bfhi(vf2.y)};
;             float o_r[4], o_k[4], o_v[4], o_a[4], o_b[4]; f32x4 o_w;
; #pragma unroll
;             for (int j = 0; j < 4; ++j) { const float r = cr_[j] + (pr_[j] - cr_[j]) * mur[j]; float v = cv_[j] + (pv_[j] - cv_[j]) * muv4[j];
;                 if (l == 1) v = v + (vf_[j] - v) * sigmoidf_(v04[j] + accv[ct][rt][j]);
.LBB0_440:
	s_waitcnt vmcnt(6)
	v_mov_b32_e32 v20, v150
	v_mov_b32_e32 v21, v151
	v_mov_b32_e32 v22, v152
	v_mov_b32_e32 v23, v153
	v_mov_b32_e32 v24, v246
	v_mov_b32_e32 v25, v247
	v_mov_b32_e32 v26, v248
	v_mov_b32_e32 v27, v249
	v_mov_b32_e32 v32, v182
	v_mov_b32_e32 v33, v183
	v_mov_b32_e32 v34, v184
	v_mov_b32_e32 v35, v185
	v_mov_b32_e32 v36, v208
	v_mov_b32_e32 v37, v209
	v_mov_b32_e32 v38, v210
	v_mov_b32_e32 v39, v211
	v_mov_b32_e32 v40, v212
	v_mov_b32_e32 v41, v213
	v_mov_b32_e32 v42, v214
	v_mov_b32_e32 v43, v215
	v_mov_b32_e32 v44, v216
	v_mov_b32_e32 v45, v217
	v_mov_b32_e32 v46, v218
	v_mov_b32_e32 v47, v219
	v_mov_b32_e32 v48, v220
	v_mov_b32_e32 v49, v221
	v_mov_b32_e32 v50, v222
	v_mov_b32_e32 v51, v223
	v_mov_b32_e32 v52, v250
	v_mov_b32_e32 v53, v251
	v_mov_b32_e32 v54, v206
	v_mov_b32_e32 v55, v207
	v_mov_b32_e32 v56, v186
	v_mov_b32_e32 v57, v187
	v_mov_b32_e32 v58, v242
	v_mov_b32_e32 v59, v243
	v_mov_b32_e32 v60, v224
	v_mov_b32_e32 v61, v225
	v_mov_b32_e32 v62, v226
	v_mov_b32_e32 v63, v227
	v_mov_b32_e32 v64, v228
	v_mov_b32_e32 v65, v229
.LBB0_444:
	global_load_dwordx4 v[182:185], v[130:131], off offset:192
	global_load_dwordx4 v[216:219], v[130:131], off offset:2240
	global_load_dwordx4 v[212:215], v[120:121], off offset:192
	global_load_dwordx4 v[208:211], v[122:123], off offset:192
	global_load_dwordx4 v[246:249], v[128:129], off offset:192
	global_load_dwordx4 v[150:153], v[124:125], off offset:192
	v_mov_b32_e32 v224, 0
	s_and_b64 vcc, exec, s[40:41]
	v_mov_b32_e32 v220, 0
	v_mov_b32_e32 v221, 0
	v_mov_b32_e32 v222, 0
	v_mov_b32_e32 v223, 0
	s_cbranch_vccnz .LBB0_456
	global_load_dwordx4 v[220:223], v[126:127], off offset:192
.LBB0_456:
	v_add_co_u32_e32 v206, vcc, 0xfffff000, v76
	global_load_dwordx2 v[186:187], v[76:77], off offset:2176
	global_load_dwordx2 v[226:227], v[76:77], off offset:3200
	v_addc_co_u32_e32 v207, vcc, -1, v77, vcc
	global_load_dwordx2 v[242:243], v[206:207], off offset:-896
	global_load_dwordx2 v[228:229], v[76:77], off offset:-3968
	v_lshl_add_u64 v[250:251], v[78:79], 0, v[88:89]
	s_and_b64 vcc, exec, s[40:41]
	v_lshl_add_u64 v[206:207], v[250:251], 1, s[50:51]
	v_mov_b32_e32 v225, 0
	s_cbranch_vccnz .Lrp_e5
	global_load_dwordx2 v[224:225], v[206:207], off
.Lrp_e5:
	v_lshlrev_b32_e32 v66, 16, v62
	v_lshlrev_b32_e32 v67, 16, v64
	v_sub_f32_e32 v67, v67, v66
	s_and_b64 vcc, exec, s[40:41]
	v_fmac_f32_e32 v66, v44, v67
	s_cbranch_vccnz .LBB0_446
	v_add_f32_e32 v28, v28, v48
	v_mul_f32_e32 v28, 0xbfb8aa3b, v28
	v_exp_f32_e32 v28, v28
	v_lshlrev_b32_e32 v44, 16, v60
	v_sub_f32_e32 v44, v44, v66
	v_add_f32_e32 v28, 1.0, v28
	v_rcp_f32_e32 v28, v28
	s_nop 0
	v_fmac_f32_e32 v66, v28, v44

; DI float sigmoidf_(float x) { return __builtin_amdgcn_rcpf(1.f + __expf(-x)); }
; DI void rwkv_prep_item(KA a, const int l, LAS unsigned char* lds, const int tile) {
;     ...
;         for (int ct = 0; ct < 4; ++ct) { const int c4 = hd * 64 + ct * 16 + 4 * fq; const size_t ro = (size_t)tk * 256 + c4;
;             const f32x4 mur = *(const f32x4*)(mu + c4), muv4 = *(const f32x4*)(mu + 512 + c4), w04 = *(const f32x4*)(w0 + c4), a04 = *(const f32x4*)(a0 + c4), kk4 = *(const f32x4*)(kkw + c4), ka4 = *(const f32x4*)(kaw + c4);
;             f32x4 v04 = ZERO4; if (l == 1) v04 = *(const f32x4*)(v0 + c4);
;             const bf16* hpr = H + (size_t)tk * HP + C_RR + c4; const bf16* hpv = H + (size_t)tk * HP + C_RV + c4;
;             const v2u cr = *(const v2u*)hpr, cv = *(const v2u*)hpv; v2u pr = {0u, 0u}, pvv = {0u, 0u}; if (!first) { pr = *(const v2u*)(hpr - HP); pvv = *(const v2u*)(hpv - HP); }
;             v2u vf2 = {0u, 0u}; if (l == 1) vf2 = *(const v2u*)(VF + ro);
;             const float cr_[4] = {bflo(cr.x), bfhi(cr.x), bflo(cr.y), bfhi(cr.y)}, pr_[4] = {bflo(pr.x), bfhi(pr.x), bflo(pr.y), bfhi(pr.y)};
;             const float cv_[4] = {bflo(cv.x), bfhi(cv.x), bflo(cv.y), bfhi(cv.y)}, pv_[4] = {bflo(pvv.x), bfhi(pvv.x), bflo(pvv.y), bfhi(pvv.y)}, vf_[4] = {bflo(vf2.x), bfhi(vf2.x), bflo(vf2.y), bfhi(vf2.y)};
;             float o_r[4], o_k[4], o_v[4], o_a[4], o_b[4]; f32x4 o_w;
; #pragma unroll
;             for (int j = 0; j < 4; ++j) { const float r = cr_[j] + (pr_[j] - cr_[j]) * mur[j]; float v = cv_[j] + (pv_[j] - cv_[j]) * muv4[j];
;                 if (l == 1) v = v + (vf_[j] - v) * sigmoidf_(v04[j] + accv[ct][rt][j]);
.LBB0_454:
	s_waitcnt vmcnt(6)
	v_mov_b32_e32 v12, v150
	v_mov_b32_e32 v13, v151
	v_mov_b32_e32 v14, v152
	v_mov_b32_e32 v15, v153
	v_mov_b32_e32 v16, v246
	v_mov_b32_e32 v17, v247
	v_mov_b32_e32 v18, v248
	v_mov_b32_e32 v19, v249
	v_mov_b32_e32 v20, v182
	v_mov_b32_e32 v21, v183
	v_mov_b32_e32 v22, v184
	v_mov_b32_e32 v23, v185
	v_mov_b32_e32 v24, v208
	v_mov_b32_e32 v25, v209
	v_mov_b32_e32 v26, v210
	v_mov_b32_e32 v27, v211
	v_mov_b32_e32 v28, v212
	v_mov_b32_e32 v29, v213
	v_mov_b32_e32 v30, v214
	v_mov_b32_e32 v31, v215
	v_mov_b32_e32 v32, v216
	v_mov_b32_e32 v33, v217
	v_mov_b32_e32 v34, v218
	v_mov_b32_e32 v35, v219
	v_mov_b32_e32 v36, v220
	v_mov_b32_e32 v37, v221
	v_mov_b32_e32 v38, v222
	v_mov_b32_e32 v39, v223
	v_mov_b32_e32 v40, v250
	v_mov_b32_e32 v41, v251
	v_mov_b32_e32 v42, v206
	v_mov_b32_e32 v43, v207
	v_mov_b32_e32 v44, v186
	v_mov_b32_e32 v45, v187
	v_mov_b32_e32 v46, v242
	v_mov_b32_e32 v47, v243
	v_mov_b32_e32 v48, v224
	v_mov_b32_e32 v49, v225
	v_mov_b32_e32 v50, v226
	v_mov_b32_e32 v51, v227
	v_mov_b32_e32 v52, v228
	v_mov_b32_e32 v53, v229
.LBB0_458:
	v_lshlrev_b32_e32 v54, 16, v50
	v_lshlrev_b32_e32 v55, 16, v52
	v_sub_f32_e32 v55, v55, v54
	s_and_b64 vcc, exec, s[40:41]
	v_fmac_f32_e32 v54, v32, v55
	s_cbranch_vccnz .LBB0_460
	v_add_f32_e32 v8, v8, v36
	v_mul_f32_e32 v8, 0xbfb8aa3b, v8
	v_exp_f32_e32 v8, v8
	v_lshlrev_b32_e32 v32, 16, v48
	v_sub_f32_e32 v32, v32, v54
	v_add_f32_e32 v8, 1.0, v8
	v_rcp_f32_e32 v8, v8
	s_nop 0
	v_fmac_f32_e32 v54, v8, v32
